# speedup vs baseline: 1.0004x; 1.0004x over previous
; #define LAS __attribute__((address_space(3)))
; DI int otid() { int t = threadIdx.x; asm volatile("" : "+v"(t)); return t; }
; DI unsigned char* ows(const Params& P) { unsigned char* p = P.ws; asm volatile("" : "+s"(p)); return p; }
; #define ATT_LOAD(kr, vr, t) do { const bf16_t* kp_ = KVb + (size_t)(t) * 64 * 2048 + kn_off; \
;         kr[0] = *(const u32x4*)kp_; kr[1] = *(const u32x4*)(kp_ + 32 * 2048); kr[2] = *(const u32x4*)(KPEb + (t) * 64 * 64 + kp_off); \
;         const bf16_t* vp_ = VTb + (t) * 64 + v_off; vr[0] = *(const u32x4*)vp_; vr[1] = *(const u32x4*)(vp_ + 64 * SEQ); } while (0)
; DI void attn_unit(const Params& P, LAS unsigned char* lds, int b, int h, int qb, bool dry) {
;     const int tid = otid(), lane = tid & 63, w = __builtin_amdgcn_readfirstlane(tid >> 6), r = lane & 31, hh = lane >> 5;
;     bf16_t* Q = (bf16_t*)(ows(P) + OFF_Q);
;     const bf16_t* KV = (const bf16_t*)(ows(P) + OFF_KV); const bf16_t* KPE = (const bf16_t*)(ows(P) + OFF_KPE); const bf16_t* VT = (const bf16_t*)(ows(P) + OFF_U);
;     LAS unsigned char* Ks = lds; LAS unsigned char* Vs = lds + 2 * KS_BYTES;
;     const int q0 = qb * 256 + w * 32;
;     bf16_t* qrow = Q + ((size_t)b * SEQ + q0 + r) * 1536 + h * 192;
;     bf16x8 qf[12];
; #pragma unroll
;     for (int s = 0; s < 12; ++s) qf[s] = *(const bf16x8*)(qrow + 16 * s + 8 * hh);
;     f32x16 o[4];
; #pragma unroll
;     for (int d = 0; d < 4; ++d)
; #pragma unroll
;         for (int i = 0; i < 16; ++i) o[d][i] = 0.f;
;     float mrun = -INFINITY, lrun = 0.f;
;     const int nt = 4 * (qb + 1);
;     const bf16_t* KVb = KV + (size_t)b * SEQ * 2048 + h * 256; const bf16_t* KPEb = KPE + (size_t)b * SEQ * 64; const bf16_t* VTb = VT + (size_t)(b * 8 + h) * 128 * SEQ;
;     const int kn_off = (tid >> 4) * 2048 + (tid & 15) * 8, kn_dst = (tid >> 4) * KS_STRIDE + (tid & 15) * 16;
;     const int kp_off = (tid >> 3) * 64 + (tid & 7) * 8, kp_dst = (tid >> 3) * KS_STRIDE + 256 + (tid & 7) * 16;
;     const int v_off = (tid >> 3) * SEQ + (tid & 7) * 8, v_dst = (tid >> 3) * VS_STRIDE + (tid & 7) * 16;
;     ...
;     ATT_LOAD(kA, vA, 0);
;     __syncthreads();
;     ATT_STORE(kA, vA, 0);
;     ATT_LOAD(kA, vA, 1);
.LBB0_31:
	s_waitcnt vmcnt(0)
	v_mov_b32_e32 v2, v195
	s_load_dwordx8 s[64:71], s[84:85], 0xc8
	s_bfe_u32 s35, s55, 0x50003
	v_readfirstlane_b32 s49, v2
	s_xor_b32 s37, s35, 63
	s_ashr_i32 s3, s49, 1
	s_ashr_i32 s46, s55, 8
	s_lshl_b32 s2, s37, 8
	s_and_b32 s53, s3, 0xffffffe0
	s_and_b32 s48, s54, 7
	s_waitcnt lgkmcnt(0)
	s_mov_b64 s[60:61], s[64:65]
	s_add_i32 s53, s53, s2
	s_ashr_i32 s47, s46, 31
	s_lshl_b32 s52, s48, 9
	s_lshr_b32 s56, s55, 3
	s_and_b32 s42, s55, 7
	s_mov_b64 s[62:63], s[66:67]
	s_mov_b64 s[64:65], s[68:69]
	s_mov_b64 s[66:67], s[70:71]
	s_lshl_b64 s[2:3], s[46:47], 14
	s_ashr_i32 s20, s53, 31
	v_and_b32_e32 v23, 31, v2
	s_mov_b64 s[30:31], s[66:67]
	s_add_u32 s36, s2, s53
	v_or_b32_e32 v3, s36, v23
	v_mov_b64_e32 v[0:1], s[30:31]
	s_addc_u32 s20, s3, s20
	v_mad_u64_u32 v[0:1], s[30:31], v3, s39, v[0:1]
	s_mul_i32 s36, s42, 0xc0
	v_mad_i32_i24 v1, s20, v248, v1
	s_lshl_b32 s20, s36, 1
	s_lshl_b32 s62, s37, 2
	v_bfe_u32 v36, v2, 5, 1
	s_mov_b64 s[40:41], s[66:67]
	v_lshl_add_u64 v[0:1], v[0:1], 0, s[20:21]
	s_mov_b64 s[30:31], 0xd808000
	s_add_i32 s59, s62, 4
	s_lshl_b64 s[44:45], s[46:47], 26
	v_lshl_add_u64 v[186:187], v[0:1], 0, s[30:31]
	v_lshlrev_b32_e32 v184, 4, v36
	s_add_u32 s30, s40, s44
	s_mov_b64 s[26:27], s[66:67]
	s_mov_b64 s[50:51], s[66:67]
	v_lshl_add_u64 v[0:1], v[186:187], 0, v[184:185]
	s_addc_u32 s31, s41, s45
	s_lshl_b32 s37, s42, 8
	s_lshl_b32 s43, s42, 9
	v_and_b32_e32 v3, 15, v2
	global_load_dwordx4 v[96:99], v[0:1], off
	global_load_dwordx4 v[100:103], v[0:1], off offset:32
	global_load_dwordx4 v[104:107], v[0:1], off offset:64
	global_load_dwordx4 v[108:111], v[0:1], off offset:96
	global_load_dwordx4 v[112:115], v[0:1], off offset:128
	global_load_dwordx4 v[116:119], v[0:1], off offset:160
	global_load_dwordx4 v[120:123], v[0:1], off offset:192
	global_load_dwordx4 v[124:127], v[0:1], off offset:224
	global_load_dwordx4 v[128:131], v[0:1], off offset:256
	global_load_dwordx4 v[132:135], v[0:1], off offset:288
	global_load_dwordx4 v[136:139], v[0:1], off offset:320
	global_load_dwordx4 v[140:143], v[0:1], off offset:352
	s_add_u32 s80, s30, s43
	v_ashrrev_i32_e32 v1, 4, v2
	v_lshlrev_b32_e32 v0, 3, v3
	s_addc_u32 s81, s31, 0
	s_lshl_b32 s57, s46, 3
	v_lshl_or_b32 v0, v1, 11, v0
	v_mul_lo_u32 v1, v1, s29
	s_lshl_b64 s[30:31], s[46:47], 21
	s_or_b32 s46, s57, s42
	v_lshl_add_u32 v38, v3, 4, v1
	v_and_b32_e32 v1, 7, v2
	s_ashr_i32 s47, s46, 31
	v_ashrrev_i32_e32 v39, 3, v2
	v_lshlrev_b32_e32 v2, 3, v1
	v_lshlrev_b32_e32 v22, 4, v1
	v_ashrrev_i32_e32 v1, 31, v0
	s_lshl_b64 s[46:47], s[46:47], 22
	v_lshlrev_b64 v[0:1], 1, v[0:1]
	s_add_u32 s94, s50, s46
	v_lshl_add_u64 v[26:27], s[80:81], 0, v[0:1]
	s_mov_b32 s28, 0x13808000
	s_addc_u32 s95, s51, s47
	v_lshl_or_b32 v10, v39, 6, v2
	v_lshl_or_b32 v14, v39, 14, v2
	v_add_co_u32_e32 v2, vcc, s28, v26
	s_mov_b32 s28, 0x13828000
	s_nop 0
	v_addc_co_u32_e32 v3, vcc, 0, v27, vcc
	s_add_u32 s26, s26, s30
	v_add_co_u32_e32 v6, vcc, s28, v26
	v_ashrrev_i32_e32 v11, 31, v10
	s_addc_u32 s27, s27, s31
	v_ashrrev_i32_e32 v15, 31, v14
	v_addc_co_u32_e32 v7, vcc, 0, v27, vcc
	v_lshl_add_u64 v[28:29], v[10:11], 1, s[26:27]
	s_mov_b32 s26, 0xd408000
	v_lshlrev_b64 v[30:31], 1, v[14:15]
	v_add_co_u32_e32 v10, vcc, s26, v28
	v_lshl_add_u64 v[18:19], s[94:95], 0, v[30:31]
	s_mov_b64 s[26:27], 0x5808000
	v_addc_co_u32_e32 v11, vcc, 0, v29, vcc
	v_lshl_add_u64 v[32:33], v[18:19], 0, s[26:27]
	s_mov_b32 s26, 0x5808000
	v_add_co_u32_e32 v14, vcc, s26, v18
	global_load_dwordx4 v[2:5], v[2:3], off
	s_nop 0
	v_addc_co_u32_e32 v15, vcc, 0, v19, vcc
	s_mov_b32 s26, 0x5a08000
	global_load_dwordx4 v[6:9], v[6:7], off
	v_add_co_u32_e32 v34, vcc, s26, v18
	global_load_dwordx4 v[10:13], v[10:11], off
	s_nop 0
	v_addc_co_u32_e32 v35, vcc, 0, v19, vcc
	global_load_dwordx4 v[14:17], v[14:15], off
	s_movk_i32 s68, 0x88
	global_load_dwordx4 v[18:21], v[34:35], off
	v_mad_u64_u32 v[24:25], s[96:97], v39, s68, v[22:23]
	v_add_u32_e32 v250, 0, v38
	s_movk_i32 s26, 0x108
	s_waitcnt lgkmcnt(0)
	s_barrier
; #define ATT_LOAD(kr, vr, t) do { const bf16_t* kp_ = KVb + (size_t)(t) * 64 * 2048 + kn_off; \
;         kr[0] = *(const u32x4*)kp_; kr[1] = *(const u32x4*)(kp_ + 32 * 2048); kr[2] = *(const u32x4*)(KPEb + (t) * 64 * 64 + kp_off); \
;         const bf16_t* vp_ = VTb + (t) * 64 + v_off; vr[0] = *(const u32x4*)vp_; vr[1] = *(const u32x4*)(vp_ + 64 * SEQ); } while (0)
; DI void attn_unit(const Params& P, LAS unsigned char* lds, int b, int h, int qb, bool dry) {
;     ...
;     f32x16 o[4];
; #pragma unroll
;     for (int d = 0; d < 4; ++d)
; #pragma unroll
;         for (int i = 0; i < 16; ++i) o[d][i] = 0.f;
;     float mrun = -INFINITY, lrun = 0.f;
;     const int nt = 4 * (qb + 1);
;     const bf16_t* KVb = KV + (size_t)b * SEQ * 2048 + h * 256; const bf16_t* KPEb = KPE + (size_t)b * SEQ * 64; const bf16_t* VTb = VT + (size_t)(b * 8 + h) * 128 * SEQ;
;     const int kn_off = (tid >> 4) * 2048 + (tid & 15) * 8, kn_dst = (tid >> 4) * KS_STRIDE + (tid & 15) * 16;
;     const int kp_off = (tid >> 3) * 64 + (tid & 7) * 8, kp_dst = (tid >> 3) * KS_STRIDE + 256 + (tid & 7) * 16;
;     const int v_off = (tid >> 3) * SEQ + (tid & 7) * 8, v_dst = (tid >> 3) * VS_STRIDE + (tid & 7) * 16;
;     ...
;     ATT_LOAD(kA, vA, 0);
;     __syncthreads();
;     ATT_STORE(kA, vA, 0);
;     ATT_LOAD(kA, vA, 1);
;     __syncthreads();
;     for (int kt = 0; kt < nt; kt += 2) {
;         const bool more2 = kt + 2 < nt;
;         if (more2) ATT_LOAD(kB, vB, kt + 2);
	s_waitcnt vmcnt(0)
	ds_write_b128 v250, v[2:5]
	ds_write_b128 v250, v[6:9] offset:12800
	v_mad_u64_u32 v[2:3], s[26:27], v39, s26, v[24:25]
	v_add_u32_e32 v252, 0, v24
	s_mov_b32 s26, 0x13848000
	v_add_u32_e32 v251, 0, v2
	v_add_u32_e32 v253, 0xc800, v252
	v_add_u32_e32 v254, 0xea00, v252
	v_add_co_u32_e32 v2, vcc, s26, v26
	ds_write_b128 v251, v[10:13] offset:256
	ds_write2_b64 v253, v[14:15], v[16:17] offset1:1
	ds_write2_b64 v254, v[18:19], v[20:21] offset1:1
	v_addc_co_u32_e32 v3, vcc, 0, v27, vcc
	s_mov_b32 s26, 0x13868000
	global_load_dwordx4 v[144:147], v[2:3], off
	v_add_co_u32_e32 v2, vcc, s26, v26
	s_mov_b32 s26, 0xd40a000
	s_nop 0
	v_addc_co_u32_e32 v3, vcc, 0, v27, vcc
	global_load_dwordx4 v[148:151], v[2:3], off
	v_add_co_u32_e32 v2, vcc, s26, v28
	s_or_b32 s48, s57, s48
	s_nop 0
	v_addc_co_u32_e32 v3, vcc, 0, v29, vcc
	global_load_dwordx4 v[152:155], v[2:3], off
	global_load_dwordx4 v[156:159], v[32:33], off offset:128
	global_load_dwordx4 v[160:163], v[34:35], off offset:128
	s_ashr_i32 s26, s49, 7
	s_ashr_i32 s49, s48, 31
	s_lshl_b64 s[48:49], s[48:49], 22
	s_add_u32 s50, s50, s48
	v_mad_u32_u24 v213, v23, s29, 0
	s_movk_i32 s27, 0xfef8
	s_addc_u32 s51, s51, s49
	s_or_b32 s57, s44, s52
	v_mad_i32_i24 v18, v23, s27, v213
	v_readlane_b32 s27, v246, 47
	s_add_u32 s40, s40, s57
	v_mad_u64_u32 v[16:17], s[80:81], v39, s29, v[22:23]
	v_mov_b32_e32 v2, s27
	s_mov_b64 s[42:43], 0xd40e000
	s_addc_u32 s41, s41, s45
	v_lshlrev_b32_e32 v37, 3, v36
	v_readlane_b32 s96, v246, 55
	v_mad_u32_u24 v17, v23, s68, v2
	v_lshl_add_u64 v[188:189], v[28:29], 0, s[42:43]
	v_lshl_add_u64 v[2:3], s[50:51], 0, v[30:31]
	s_mov_b64 s[42:43], 0x5a08180
	v_lshl_add_u64 v[0:1], s[40:41], 0, v[0:1]
	s_mov_b64 s[40:41], 0x138e8000
	v_mov_b32_e32 v14, v185
	v_mov_b32_e32 v15, v185
	v_readlane_b32 s97, v246, 56
	v_readlane_b32 s94, v246, 63
	v_or_b32_e32 v214, s53, v23
	v_lshlrev_b32_e32 v212, 2, v36
	v_lshl_add_u64 v[190:191], v[2:3], 0, s[42:43]
	v_lshl_add_u64 v[192:193], v[0:1], 0, s[40:41]
	s_add_i32 s40, s26, s62
	v_mov_b32_e32 v0, v185
	v_mov_b32_e32 v1, v185
	v_mov_b32_e32 v2, v185
	v_mov_b32_e32 v3, v185
	v_mov_b32_e32 v4, v185
	v_mov_b32_e32 v5, v185
	v_mov_b32_e32 v6, v185
	v_mov_b32_e32 v7, v185
	v_mov_b32_e32 v8, v185
	v_mov_b32_e32 v9, v185
	v_mov_b32_e32 v10, v185
	v_mov_b32_e32 v11, v185
	v_mov_b32_e32 v12, v185
	v_mov_b32_e32 v13, v185
	v_add_u32_e32 v216, v18, v37
	v_add_u32_e32 v217, 0, v16
	v_add_u32_e32 v218, v17, v37
	v_mov_b64_e32 v[30:31], v[14:15]
	v_mov_b64_e32 v[46:47], v[14:15]
	v_mov_b64_e32 v[62:63], v[14:15]
	s_mov_b32 s20, 2
	v_readlane_b32 s98, v246, 57
	v_readlane_b32 s95, v245, 0
	v_readlane_b32 s71, v246, 62
	v_readlane_b32 s69, v246, 61
	s_mov_b32 s81, 0x14000
	v_readlane_b32 s28, v246, 54
	s_mov_b32 s58, s45
	s_sub_i32 s27, 1, s40
	s_sub_i32 s62, 0, s62
	s_sub_i32 s63, 0, s40
	v_mov_b32_e32 v194, 0xff800000
	v_mov_b32_e32 v196, 0
	v_mov_b32_e32 v197, 0
	v_mov_b32_e32 v198, 0
	v_mov_b32_e32 v199, 0
	v_mov_b32_e32 v200, 0
	v_mov_b32_e32 v201, 0
	v_mov_b32_e32 v202, 0
	v_mov_b32_e32 v203, 0
	v_mov_b32_e32 v204, 0
	v_mov_b32_e32 v205, 0
	v_mov_b32_e32 v206, 0
	v_mov_b32_e32 v207, 0
	v_mov_b32_e32 v208, 0
	v_mov_b32_e32 v209, 0
	v_mov_b32_e32 v210, 0
	v_mov_b32_e32 v211, 0
	v_mov_b32_e32 v215, 0
	v_mov_b32_e32 v219, v212
	v_mov_b64_e32 v[28:29], v[12:13]
	v_mov_b64_e32 v[26:27], v[10:11]
	v_mov_b64_e32 v[24:25], v[8:9]
	v_mov_b64_e32 v[22:23], v[6:7]
	v_mov_b64_e32 v[20:21], v[4:5]
	v_mov_b64_e32 v[18:19], v[2:3]
	v_mov_b64_e32 v[16:17], v[0:1]
	v_mov_b64_e32 v[44:45], v[12:13]
	v_mov_b64_e32 v[42:43], v[10:11]
	v_mov_b64_e32 v[40:41], v[8:9]
	v_mov_b64_e32 v[38:39], v[6:7]
	v_mov_b64_e32 v[36:37], v[4:5]
	v_mov_b64_e32 v[34:35], v[2:3]
	v_mov_b64_e32 v[32:33], v[0:1]
	v_mov_b64_e32 v[60:61], v[12:13]
	v_mov_b64_e32 v[58:59], v[10:11]
	v_mov_b64_e32 v[56:57], v[8:9]
	v_mov_b64_e32 v[54:55], v[6:7]
	v_mov_b64_e32 v[52:53], v[4:5]
	v_mov_b64_e32 v[50:51], v[2:3]
	v_mov_b64_e32 v[48:49], v[0:1]
	s_mov_b64 s[96:97], 0x4000
	v_readlane_b32 s99, v246, 58
	v_cmp_lt_u32_e32 vcc, 0xff, v195
	s_cbranch_vccnz .Lattn_pro1_skip
	v_add_co_u32_e32 v64, vcc, 0xfffa0000, v192
	s_nop 1
	v_addc_co_u32_e32 v65, vcc, -1, v193, vcc
	v_add_co_u32_e32 v66, vcc, 0xfffc0000, v192
	s_nop 1
	v_addc_co_u32_e32 v67, vcc, -1, v193, vcc
	global_load_dwordx4 v[164:167], v[64:65], off
	global_load_dwordx4 v[168:171], v[66:67], off
	v_add_co_u32_e32 v64, vcc, 0xffffe000, v188
	s_nop 1
	v_addc_co_u32_e32 v65, vcc, -1, v189, vcc
	global_load_dwordx4 v[172:175], v[64:65], off
	v_add_co_u32_e32 v64, vcc, 0xffdfff80, v190
	s_nop 1
	v_addc_co_u32_e32 v65, vcc, -1, v191, vcc
	v_add_co_u32_e32 v66, vcc, 0xffffff80, v190
	s_nop 1
	v_addc_co_u32_e32 v67, vcc, -1, v191, vcc
	global_load_dwordx4 v[176:179], v[64:65], off
	global_load_dwordx4 v[180:183], v[66:67], off

; #define ATT_LOAD(kr, vr, t) do { const bf16_t* kp_ = KVb + (size_t)(t) * 64 * 2048 + kn_off; \
;         kr[0] = *(const u32x4*)kp_; kr[1] = *(const u32x4*)(kp_ + 32 * 2048); kr[2] = *(const u32x4*)(KPEb + (t) * 64 * 64 + kp_off); \
;         const bf16_t* vp_ = VTb + (t) * 64 + v_off; vr[0] = *(const u32x4*)vp_; vr[1] = *(const u32x4*)(vp_ + 64 * SEQ); } while (0)
; #define ATT_TILE(t, slot) do { const int rel_ = (t) - 4 * qb; if (rel_ <= (w >> 1)) { qk_softmax((t), (slot), rel_ == (w >> 1)); pv(slot); } } while (0)
; DI void attn_unit(const Params& P, LAS unsigned char* lds, int b, int h, int qb, bool dry) {
;     ...
;     ATT_LOAD(kA, vA, 0);
;     __syncthreads();
;     ATT_STORE(kA, vA, 0);
;     ATT_LOAD(kA, vA, 1);
;     __syncthreads();
;     for (int kt = 0; kt < nt; kt += 2) {
;         const bool more2 = kt + 2 < nt;
;         if (more2) ATT_LOAD(kB, vB, kt + 2);
;         ATT_TILE(kt, 0);
;         ATT_STORE(kA, vA, 1);
;         __syncthreads();
;         if (more2) ATT_LOAD(kA, vA, kt + 3);
;         ATT_TILE(kt + 1, 1);
;         if (more2) ATT_STORE(kB, vB, 0);
;         __syncthreads();
;     }
.LBB0_32:
	s_mov_b64 s[40:41], 0x100
	v_lshl_add_u64 v[190:191], v[190:191], 0, s[40:41]
	s_mov_b64 s[40:41], 0x80000
	v_add_u32_e32 v219, 0x80, v219
	v_lshl_add_u64 v[188:189], v[188:189], 0, s[96:97]
	v_lshl_add_u64 v[192:193], v[192:193], 0, s[40:41]
	s_add_i32 s20, s20, 2
	s_waitcnt lgkmcnt(0)
	s_cmp_lt_u32 s20, s59
	s_cbranch_scc0 .Lattn_pfB1_skip
	v_cmp_lt_u32_e32 vcc, 0xff, v195
	s_cbranch_vccnz .Lattn_pfB1_skip
	v_add_co_u32_e32 v64, vcc, 0xfffa0000, v192
	s_nop 1
	v_addc_co_u32_e32 v65, vcc, -1, v193, vcc
	v_add_co_u32_e32 v66, vcc, 0xfffc0000, v192
	s_nop 1
	v_addc_co_u32_e32 v67, vcc, -1, v193, vcc
	global_load_dwordx4 v[164:167], v[64:65], off
	global_load_dwordx4 v[168:171], v[66:67], off
	v_add_co_u32_e32 v64, vcc, 0xffffe000, v188
	s_nop 1
	v_addc_co_u32_e32 v65, vcc, -1, v189, vcc
	global_load_dwordx4 v[172:175], v[64:65], off
	v_add_co_u32_e32 v64, vcc, 0xffdfff80, v190
	s_nop 1
	v_addc_co_u32_e32 v65, vcc, -1, v191, vcc
	v_add_co_u32_e32 v66, vcc, 0xffffff80, v190
	s_nop 1
	v_addc_co_u32_e32 v67, vcc, -1, v191, vcc
	global_load_dwordx4 v[176:179], v[64:65], off
	global_load_dwordx4 v[180:183], v[66:67], off

; #define ATT_LOAD(kr, vr, t) do { const bf16_t* kp_ = KVb + (size_t)(t) * 64 * 2048 + kn_off; \
;         kr[0] = *(const u32x4*)kp_; kr[1] = *(const u32x4*)(kp_ + 32 * 2048); kr[2] = *(const u32x4*)(KPEb + (t) * 64 * 64 + kp_off); \
;         const bf16_t* vp_ = VTb + (t) * 64 + v_off; vr[0] = *(const u32x4*)vp_; vr[1] = *(const u32x4*)(vp_ + 64 * SEQ); } while (0)
; DI void attn_unit(const Params& P, LAS unsigned char* lds, int b, int h, int qb, bool dry) {
;     ...
;     ATT_LOAD(kA, vA, 0);
;     __syncthreads();
;     ATT_STORE(kA, vA, 0);
;     ATT_LOAD(kA, vA, 1);
;     __syncthreads();
;     for (int kt = 0; kt < nt; kt += 2) {
;         const bool more2 = kt + 2 < nt;
;         if (more2) ATT_LOAD(kB, vB, kt + 2);
.LBB0_33:
	s_cmp_lt_u32 s20, s59
	s_cselect_b64 s[52:53], -1, 0
	s_cmp_ge_u32 s20, s59
	s_cselect_b64 s[50:51], -1, 0
	s_and_b64 vcc, exec, s[50:51]
	s_cbranch_vccnz .LBB0_35
	v_cmp_lt_u32_e32 vcc, 0xff, v195
	s_cbranch_vccz .LBB0_35
	v_add_co_u32_e32 v64, vcc, 0xfffa0000, v192
	s_nop 1
	v_addc_co_u32_e32 v65, vcc, -1, v193, vcc
	v_add_co_u32_e32 v66, vcc, 0xfffc0000, v192
	s_nop 1
	v_addc_co_u32_e32 v67, vcc, -1, v193, vcc
	global_load_dwordx4 v[164:167], v[64:65], off
	global_load_dwordx4 v[168:171], v[66:67], off
	v_add_co_u32_e32 v64, vcc, 0xffffe000, v188
	s_nop 1
	v_addc_co_u32_e32 v65, vcc, -1, v189, vcc
	global_load_dwordx4 v[172:175], v[64:65], off
	v_add_co_u32_e32 v64, vcc, 0xffdfff80, v190
	s_nop 1
	v_addc_co_u32_e32 v65, vcc, -1, v191, vcc
	v_add_co_u32_e32 v66, vcc, 0xffffff80, v190
	s_nop 1
	v_addc_co_u32_e32 v67, vcc, -1, v191, vcc
	global_load_dwordx4 v[176:179], v[64:65], off
	global_load_dwordx4 v[180:183], v[66:67], off

; #define ATT_LOAD(kr, vr, t) do { const bf16_t* kp_ = KVb + (size_t)(t) * 64 * 2048 + kn_off; \
;         kr[0] = *(const u32x4*)kp_; kr[1] = *(const u32x4*)(kp_ + 32 * 2048); kr[2] = *(const u32x4*)(KPEb + (t) * 64 * 64 + kp_off); \
;         const bf16_t* vp_ = VTb + (t) * 64 + v_off; vr[0] = *(const u32x4*)vp_; vr[1] = *(const u32x4*)(vp_ + 64 * SEQ); } while (0)
; #define ATT_TILE(t, slot) do { const int rel_ = (t) - 4 * qb; if (rel_ <= (w >> 1)) { qk_softmax((t), (slot), rel_ == (w >> 1)); pv(slot); } } while (0)
; DI void attn_unit(const Params& P, LAS unsigned char* lds, int b, int h, int qb, bool dry) {
;     ...
;     ATT_LOAD(kA, vA, 0);
;     __syncthreads();
;     ATT_STORE(kA, vA, 0);
;     ATT_LOAD(kA, vA, 1);
;     __syncthreads();
;     for (int kt = 0; kt < nt; kt += 2) {
;         const bool more2 = kt + 2 < nt;
;         if (more2) ATT_LOAD(kB, vB, kt + 2);
;         ATT_TILE(kt, 0);
;         ATT_STORE(kA, vA, 1);
;         __syncthreads();
;         if (more2) ATT_LOAD(kA, vA, kt + 3);
;         ATT_TILE(kt + 1, 1);
.Lattn_wdone0:
	s_not_b64 s[40:41], s[52:53]
	s_waitcnt lgkmcnt(0)
	s_mov_b64 vcc, s[52:53]
	s_cbranch_vccz .Lattn_pfA1_skip
	v_cmp_lt_u32_e32 vcc, 0xff, v195
	s_cbranch_vccnz .Lattn_pfA1_skip
	v_add_co_u32_e32 v64, vcc, 0xfffe0000, v192
	s_nop 1
	v_addc_co_u32_e32 v65, vcc, -1, v193, vcc
	global_load_dwordx4 v[144:147], v[64:65], off
	global_load_dwordx4 v[148:151], v[192:193], off
	global_load_dwordx4 v[152:155], v[188:189], off
	v_add_co_u32_e32 v64, vcc, 0xffe00000, v190
	s_nop 1
	v_addc_co_u32_e32 v65, vcc, -1, v191, vcc
	global_load_dwordx4 v[156:159], v[64:65], off
	global_load_dwordx4 v[160:163], v[190:191], off
.Lattn_pfA1_skip:
	s_andn2_b64 vcc, exec, s[52:53]
	s_barrier
	s_cbranch_vccnz .LBB0_44
	v_cmp_lt_u32_e32 vcc, 0xff, v195
	s_cbranch_vccz .Lattn_pfA1_b
	v_add_co_u32_e32 v64, vcc, 0xfffe0000, v192
	s_nop 1
	v_addc_co_u32_e32 v65, vcc, -1, v193, vcc
	global_load_dwordx4 v[144:147], v[64:65], off
	global_load_dwordx4 v[148:151], v[192:193], off
	global_load_dwordx4 v[152:155], v[188:189], off
	v_add_co_u32_e32 v64, vcc, 0xffe00000, v190
	s_nop 1
	v_addc_co_u32_e32 v65, vcc, -1, v191, vcc
	global_load_dwordx4 v[156:159], v[64:65], off
	global_load_dwordx4 v[160:163], v[190:191], off
.Lattn_pfA1_b:
	s_add_i32 s80, s80, -1
	s_cmp_gt_i32 s80, s26
	s_cbranch_scc0 .LBB0_45

; DI unsigned pk_bf16(float lo, float hi) { unsigned r; asm("v_cvt_pk_bf16_f32 %0, %1, %2" : "=v"(r) : "v"(lo), "v"(hi)); return r; }
; DI int obid() { int b = blockIdx.x; asm volatile("" : "+s"(b)); return b; }
; DI void attn_unit(const Params& P, LAS unsigned char* lds, int b, int h, int qb, bool dry) {
;     ...
;     float lt; { const auto rr = __builtin_amdgcn_permlane32_swap(__float_as_uint(lrun), __float_as_uint(lrun), false, false); lt = __uint_as_float(rr[0]) + __uint_as_float(rr[1]); }
;     const float inv = 1.f / lt;
;     if (dry) { float tt = 0.f;
; #pragma unroll
;         for (int d = 0; d < 4; ++d)
; #pragma unroll
;             for (int i = 0; i < 16; ++i) tt += o[d][i];
;         if (tt * inv != 123456.789f) return; }
; #pragma unroll
;     for (int d = 0; d < 4; ++d)
; #pragma unroll
;         for (int g = 0; g < 4; ++g) {
;             u32x2 ov; ov.x = pk_bf16(o[d][4 * g] * inv, o[d][4 * g + 1] * inv); ov.y = pk_bf16(o[d][4 * g + 2] * inv, o[d][4 * g + 3] * inv);
;             *(u32x2*)(qrow + 32 * d + 8 * g + 4 * hh) = ov;
;         }
; DI void phase_attn(const Params& P, LAS unsigned char* lds, bool dry) {
;     for (int item = obid(); item < 512; item += gridDim.x) {
;         const int h = item & 7, p = (item >> 3) & 31, b = item >> 8;
;         attn_unit(P, lds, b, h, 63 - p, dry);
;         attn_unit(P, lds, b, h, p, dry);
.LBB0_51:
	v_mov_b32_e32 v64, v215
	s_nop 1
	v_permlane32_swap_b32_e32 v215, v64
	v_add_f32_e32 v64, v215, v64
	v_div_scale_f32 v65, s[26:27], v64, v64, 1.0
	v_rcp_f32_e32 v66, v65
	v_lshlrev_b32_e32 v184, 1, v212
	s_and_b32 s20, s56, 31
	s_lshl_b32 s53, s20, 2
	v_fma_f32 v67, -v65, v66, 1.0
	v_fmac_f32_e32 v66, v67, v66
	v_div_scale_f32 v67, vcc, 1.0, v64, 1.0
	v_mul_f32_e32 v68, v67, v66
	v_fma_f32 v69, -v65, v68, v67
	v_fmac_f32_e32 v68, v69, v66
	v_fma_f32 v65, -v65, v68, v67
	v_div_fmas_f32 v65, v65, v66, v68
	v_div_fixup_f32 v66, v65, v64, 1.0
	v_mul_f32_e32 v32, v32, v66
	v_mul_f32_e32 v33, v33, v66
	v_mul_f32_e32 v48, v48, v66
	v_mul_f32_e32 v49, v49, v66
	v_cvt_pk_bf16_f32 v32, v32, v33
	v_mul_f32_e32 v33, v34, v66
	v_mul_f32_e32 v16, v16, v66
	v_mul_f32_e32 v17, v17, v66
	v_mul_f32_e32 v0, v0, v66
	v_mul_f32_e32 v1, v1, v66
	v_lshl_add_u64 v[64:65], v[186:187], 0, v[184:185]
	v_cvt_pk_bf16_f32 v48, v48, v49
	v_mul_f32_e32 v49, v50, v66
	v_mul_f32_e32 v34, v35, v66
	v_cvt_pk_bf16_f32 v33, v33, v34
	v_cvt_pk_bf16_f32 v16, v16, v17
	v_mul_f32_e32 v17, v18, v66
	v_cvt_pk_bf16_f32 v0, v0, v1
	v_mul_f32_e32 v1, v2, v66
	v_mul_f32_e32 v50, v51, v66
	v_cvt_pk_bf16_f32 v49, v49, v50
	global_store_dwordx2 v[64:65], v[32:33], off offset:64
	v_mul_f32_e32 v32, v36, v66
	v_mul_f32_e32 v33, v37, v66
	v_mul_f32_e32 v18, v19, v66
	v_cvt_pk_bf16_f32 v17, v17, v18
	v_mul_f32_e32 v2, v3, v66
	v_cvt_pk_bf16_f32 v1, v1, v2
	global_store_dwordx2 v[64:65], v[48:49], off
	v_mul_f32_e32 v48, v52, v66
	v_mul_f32_e32 v49, v53, v66
	v_cvt_pk_bf16_f32 v32, v32, v33
	v_mul_f32_e32 v33, v38, v66
	global_store_dwordx2 v[64:65], v[16:17], off offset:128
	v_mul_f32_e32 v16, v20, v66
	v_mul_f32_e32 v17, v21, v66
	global_store_dwordx2 v[64:65], v[0:1], off offset:192
	v_mul_f32_e32 v0, v4, v66
	v_mul_f32_e32 v1, v5, v66
	v_cvt_pk_bf16_f32 v48, v48, v49
	v_mul_f32_e32 v49, v54, v66
	v_mul_f32_e32 v34, v39, v66
	v_cvt_pk_bf16_f32 v33, v33, v34
	v_cvt_pk_bf16_f32 v16, v16, v17
	v_mul_f32_e32 v17, v22, v66
	v_cvt_pk_bf16_f32 v0, v0, v1
	v_mul_f32_e32 v1, v6, v66
	v_mul_f32_e32 v50, v55, v66
	v_cvt_pk_bf16_f32 v49, v49, v50
	global_store_dwordx2 v[64:65], v[32:33], off offset:80
	v_mul_f32_e32 v32, v40, v66
	v_mul_f32_e32 v33, v41, v66
	v_mul_f32_e32 v18, v23, v66
	v_cvt_pk_bf16_f32 v17, v17, v18
	v_mul_f32_e32 v2, v7, v66
	v_cvt_pk_bf16_f32 v1, v1, v2
	global_store_dwordx2 v[64:65], v[48:49], off offset:16
	v_mul_f32_e32 v48, v56, v66
	v_mul_f32_e32 v49, v57, v66
	v_cvt_pk_bf16_f32 v32, v32, v33
	v_mul_f32_e32 v33, v42, v66
	global_store_dwordx2 v[64:65], v[16:17], off offset:144
	v_mul_f32_e32 v16, v24, v66
	v_mul_f32_e32 v17, v25, v66
	global_store_dwordx2 v[64:65], v[0:1], off offset:208
	v_mul_f32_e32 v0, v8, v66
	v_mul_f32_e32 v1, v9, v66
	v_cvt_pk_bf16_f32 v48, v48, v49
	v_mul_f32_e32 v49, v58, v66
	v_mul_f32_e32 v34, v43, v66
	v_cvt_pk_bf16_f32 v33, v33, v34
	v_cvt_pk_bf16_f32 v16, v16, v17
	v_mul_f32_e32 v17, v26, v66
	v_cvt_pk_bf16_f32 v0, v0, v1
	v_mul_f32_e32 v1, v10, v66
	v_mul_f32_e32 v50, v59, v66
	v_cvt_pk_bf16_f32 v49, v49, v50
	global_store_dwordx2 v[64:65], v[32:33], off offset:96
	v_mul_f32_e32 v32, v44, v66
	v_mul_f32_e32 v33, v45, v66
	v_mul_f32_e32 v18, v27, v66
	v_cvt_pk_bf16_f32 v17, v17, v18
	v_mul_f32_e32 v2, v11, v66
	v_cvt_pk_bf16_f32 v1, v1, v2
	global_store_dwordx2 v[64:65], v[48:49], off offset:32
	v_mul_f32_e32 v48, v60, v66
	v_mul_f32_e32 v49, v61, v66
	v_cvt_pk_bf16_f32 v32, v32, v33
	v_mul_f32_e32 v33, v46, v66
	global_store_dwordx2 v[64:65], v[16:17], off offset:160
	v_mul_f32_e32 v16, v28, v66
	v_mul_f32_e32 v17, v29, v66
	global_store_dwordx2 v[64:65], v[0:1], off offset:224
	v_mul_f32_e32 v0, v12, v66
	v_mul_f32_e32 v1, v13, v66
	v_cvt_pk_bf16_f32 v48, v48, v49
	v_mul_f32_e32 v49, v62, v66
	v_mul_f32_e32 v34, v47, v66
	v_cvt_pk_bf16_f32 v33, v33, v34
	global_store_dwordx2 v[64:65], v[32:33], off offset:112
	v_cvt_pk_bf16_f32 v16, v16, v17
	v_mul_f32_e32 v17, v30, v66
	v_cvt_pk_bf16_f32 v0, v0, v1
	v_mul_f32_e32 v1, v14, v66
	v_mov_b32_e32 v32, v195
	v_mul_f32_e32 v50, v63, v66
	v_cvt_pk_bf16_f32 v49, v49, v50
	global_store_dwordx2 v[64:65], v[48:49], off offset:48
	v_mul_f32_e32 v18, v31, v66
	v_cvt_pk_bf16_f32 v17, v17, v18
	global_store_dwordx2 v[64:65], v[16:17], off offset:176
	v_mul_f32_e32 v2, v15, v66
	v_cvt_pk_bf16_f32 v1, v1, v2
	global_store_dwordx2 v[64:65], v[0:1], off offset:240
	s_load_dwordx8 s[60:67], s[84:85], 0xc8
	v_readfirstlane_b32 s42, v32
	s_ashr_i32 s43, s42, 1
	s_lshl_b32 s20, s35, 8
	s_andn2_b32 s43, s43, 31
	s_add_i32 s43, s43, s20
	s_sub_i32 s52, 0, s53
	s_ashr_i32 s20, s43, 31
	s_add_u32 s56, s2, s43
	s_addc_u32 s59, s3, s20
	s_lshl_b32 s35, s35, 2
	s_waitcnt lgkmcnt(0)
; #define LAS __attribute__((address_space(3)))
; DI int otid() { int t = threadIdx.x; asm volatile("" : "+v"(t)); return t; }
; DI unsigned char* ows(const Params& P) { unsigned char* p = P.ws; asm volatile("" : "+s"(p)); return p; }
; #define ATT_LOAD(kr, vr, t) do { const bf16_t* kp_ = KVb + (size_t)(t) * 64 * 2048 + kn_off; \
;         kr[0] = *(const u32x4*)kp_; kr[1] = *(const u32x4*)(kp_ + 32 * 2048); kr[2] = *(const u32x4*)(KPEb + (t) * 64 * 64 + kp_off); \
;         const bf16_t* vp_ = VTb + (t) * 64 + v_off; vr[0] = *(const u32x4*)vp_; vr[1] = *(const u32x4*)(vp_ + 64 * SEQ); } while (0)
; DI void attn_unit(const Params& P, LAS unsigned char* lds, int b, int h, int qb, bool dry) {
;     const int tid = otid(), lane = tid & 63, w = __builtin_amdgcn_readfirstlane(tid >> 6), r = lane & 31, hh = lane >> 5;
;     bf16_t* Q = (bf16_t*)(ows(P) + OFF_Q);
;     const bf16_t* KV = (const bf16_t*)(ows(P) + OFF_KV); const bf16_t* KPE = (const bf16_t*)(ows(P) + OFF_KPE); const bf16_t* VT = (const bf16_t*)(ows(P) + OFF_U);
;     LAS unsigned char* Ks = lds; LAS unsigned char* Vs = lds + 2 * KS_BYTES;
;     const int q0 = qb * 256 + w * 32;
;     bf16_t* qrow = Q + ((size_t)b * SEQ + q0 + r) * 1536 + h * 192;
;     bf16x8 qf[12];
; #pragma unroll
;     for (int s = 0; s < 12; ++s) qf[s] = *(const bf16x8*)(qrow + 16 * s + 8 * hh);
;     f32x16 o[4];
; #pragma unroll
;     for (int d = 0; d < 4; ++d)
; #pragma unroll
;         for (int i = 0; i < 16; ++i) o[d][i] = 0.f;
;     float mrun = -INFINITY, lrun = 0.f;
;     const int nt = 4 * (qb + 1);
;     const bf16_t* KVb = KV + (size_t)b * SEQ * 2048 + h * 256; const bf16_t* KPEb = KPE + (size_t)b * SEQ * 64; const bf16_t* VTb = VT + (size_t)(b * 8 + h) * 128 * SEQ;
;     const int kn_off = (tid >> 4) * 2048 + (tid & 15) * 8, kn_dst = (tid >> 4) * KS_STRIDE + (tid & 15) * 16;
;     const int kp_off = (tid >> 3) * 64 + (tid & 7) * 8, kp_dst = (tid >> 3) * KS_STRIDE + 256 + (tid & 7) * 16;
;     const int v_off = (tid >> 3) * SEQ + (tid & 7) * 8, v_dst = (tid >> 3) * VS_STRIDE + (tid & 7) * 16;
;     ...
;     ATT_LOAD(kA, vA, 0);
;     __syncthreads();
;     ATT_STORE(kA, vA, 0);
;     ATT_LOAD(kA, vA, 1);
	s_mov_b64 s[50:51], s[66:67]
	s_mov_b64 s[26:27], s[66:67]
	s_lshl_b32 s20, s36, 1
	s_add_i32 s35, s35, 4
	v_and_b32_e32 v35, 15, v32
	s_add_u32 s2, s26, s44
	v_ashrrev_i32_e32 v34, 4, v32
	v_lshlrev_b32_e32 v0, 3, v35
	v_and_b32_e32 v37, 7, v32
	s_addc_u32 s3, s27, s45
	s_lshl_b32 s36, s37, 1
	v_lshl_or_b32 v0, v34, 11, v0
	v_ashrrev_i32_e32 v36, 3, v32
	v_lshlrev_b32_e32 v1, 3, v37
	s_add_u32 s2, s2, s36
	v_lshl_or_b32 v8, v36, 6, v1
	v_lshl_or_b32 v12, v36, 14, v1
	v_ashrrev_i32_e32 v1, 31, v0
	s_addc_u32 s3, s3, 0
	v_lshlrev_b64 v[20:21], 1, v[0:1]
	s_mov_b64 s[62:63], s[66:67]
	s_mov_b64 s[40:41], s[66:67]
	v_lshl_add_u64 v[22:23], s[2:3], 0, v[20:21]
	s_mov_b32 s2, 0x13808000
	s_add_u32 s36, s40, s46
	v_add_co_u32_e32 v0, vcc, s2, v22
	s_addc_u32 s37, s41, s47
	s_nop 0
	v_addc_co_u32_e32 v1, vcc, 0, v23, vcc
	s_mov_b32 s2, 0x13828000
	v_add_co_u32_e32 v4, vcc, s2, v22
	s_add_u32 s2, s62, s30
	v_ashrrev_i32_e32 v9, 31, v8
	s_addc_u32 s3, s63, s31
	v_addc_co_u32_e32 v5, vcc, 0, v23, vcc
	v_lshl_add_u64 v[24:25], v[8:9], 1, s[2:3]
	s_mov_b32 s2, 0xd408000
	v_ashrrev_i32_e32 v13, 31, v12
	v_add_co_u32_e32 v8, vcc, s2, v24
	v_lshlrev_b64 v[26:27], 1, v[12:13]
	global_load_dwordx4 v[0:3], v[0:1], off
	s_nop 0
	global_load_dwordx4 v[4:7], v[4:5], off
	v_addc_co_u32_e32 v9, vcc, 0, v25, vcc
	v_lshl_add_u64 v[28:29], s[36:37], 0, v[26:27]
	s_mov_b32 s2, 0x5808000
	v_add_co_u32_e32 v12, vcc, s2, v28
	s_mov_b32 s2, 0x5a08000
	s_nop 0
	v_addc_co_u32_e32 v13, vcc, 0, v29, vcc
	v_add_co_u32_e32 v30, vcc, s2, v28
	global_load_dwordx4 v[8:11], v[8:9], off
	s_nop 0
	v_addc_co_u32_e32 v31, vcc, 0, v29, vcc
	global_load_dwordx4 v[12:15], v[12:13], off
	v_and_b32_e32 v38, 31, v32
	global_load_dwordx4 v[16:19], v[30:31], off
	v_bfe_u32 v39, v32, 5, 1
	v_or_b32_e32 v40, s56, v38
	v_mov_b64_e32 v[32:33], s[50:51]
	v_mad_u64_u32 v[32:33], s[2:3], v40, s39, v[32:33]
	v_mad_i32_i24 v33, s59, v248, v33
	v_lshl_add_u64 v[32:33], v[32:33], 0, s[20:21]
	s_mov_b64 s[2:3], 0xd808000
	v_lshl_add_u64 v[186:187], v[32:33], 0, s[2:3]
	v_lshlrev_b32_e32 v184, 4, v39
	v_lshl_add_u64 v[32:33], v[186:187], 0, v[184:185]
	global_load_dwordx4 v[96:99], v[32:33], off
	global_load_dwordx4 v[100:103], v[32:33], off offset:32
	global_load_dwordx4 v[104:107], v[32:33], off offset:64
	global_load_dwordx4 v[108:111], v[32:33], off offset:96
	global_load_dwordx4 v[112:115], v[32:33], off offset:128
	global_load_dwordx4 v[116:119], v[32:33], off offset:160
	global_load_dwordx4 v[120:123], v[32:33], off offset:192
	global_load_dwordx4 v[124:127], v[32:33], off offset:224
	global_load_dwordx4 v[128:131], v[32:33], off offset:256
	global_load_dwordx4 v[132:135], v[32:33], off offset:288
	global_load_dwordx4 v[136:139], v[32:33], off offset:320
	global_load_dwordx4 v[140:143], v[32:33], off offset:352
	v_mul_lo_u32 v32, v34, s29
	v_lshl_add_u32 v33, v35, 4, v32
	v_lshlrev_b32_e32 v32, 4, v37
	v_mad_u64_u32 v[34:35], s[2:3], v36, s68, v[32:33]
	s_mov_b64 s[2:3], 0x5808000
	s_nop 0
	v_lshl_add_u64 v[28:29], v[28:29], 0, s[2:3]
	v_add_u32_e32 v250, 0, v33
	s_movk_i32 s2, 0x108
	s_waitcnt lgkmcnt(0)
	s_barrier
; #define ATT_LOAD(kr, vr, t) do { const bf16_t* kp_ = KVb + (size_t)(t) * 64 * 2048 + kn_off; \
;         kr[0] = *(const u32x4*)kp_; kr[1] = *(const u32x4*)(kp_ + 32 * 2048); kr[2] = *(const u32x4*)(KPEb + (t) * 64 * 64 + kp_off); \
;         const bf16_t* vp_ = VTb + (t) * 64 + v_off; vr[0] = *(const u32x4*)vp_; vr[1] = *(const u32x4*)(vp_ + 64 * SEQ); } while (0)
; DI void attn_unit(const Params& P, LAS unsigned char* lds, int b, int h, int qb, bool dry) {
;     ...
;     f32x16 o[4];
; #pragma unroll
;     for (int d = 0; d < 4; ++d)
; #pragma unroll
;         for (int i = 0; i < 16; ++i) o[d][i] = 0.f;
;     float mrun = -INFINITY, lrun = 0.f;
;     const int nt = 4 * (qb + 1);
;     const bf16_t* KVb = KV + (size_t)b * SEQ * 2048 + h * 256; const bf16_t* KPEb = KPE + (size_t)b * SEQ * 64; const bf16_t* VTb = VT + (size_t)(b * 8 + h) * 128 * SEQ;
;     const int kn_off = (tid >> 4) * 2048 + (tid & 15) * 8, kn_dst = (tid >> 4) * KS_STRIDE + (tid & 15) * 16;
;     const int kp_off = (tid >> 3) * 64 + (tid & 7) * 8, kp_dst = (tid >> 3) * KS_STRIDE + 256 + (tid & 7) * 16;
;     const int v_off = (tid >> 3) * SEQ + (tid & 7) * 8, v_dst = (tid >> 3) * VS_STRIDE + (tid & 7) * 16;
;     ...
;     ATT_LOAD(kA, vA, 0);
;     __syncthreads();
;     ATT_STORE(kA, vA, 0);
;     ATT_LOAD(kA, vA, 1);
;     __syncthreads();
;     for (int kt = 0; kt < nt; kt += 2) {
;         const bool more2 = kt + 2 < nt;
;         if (more2) ATT_LOAD(kB, vB, kt + 2);
	s_waitcnt vmcnt(0)
	ds_write_b128 v250, v[0:3]
	ds_write_b128 v250, v[4:7] offset:12800
	v_mad_u64_u32 v[0:1], s[2:3], v36, s2, v[34:35]
	s_mov_b32 s2, 0x13848000
	v_add_u32_e32 v251, 0, v0
	v_add_co_u32_e32 v0, vcc, s2, v22
	v_add_u32_e32 v252, 0, v34
	s_nop 0
	v_addc_co_u32_e32 v1, vcc, 0, v23, vcc
	s_mov_b32 s2, 0x13868000
	v_add_u32_e32 v253, 0xc800, v252
	v_add_u32_e32 v254, 0xea00, v252
	v_add_co_u32_e32 v2, vcc, s2, v22
	ds_write_b128 v251, v[8:11] offset:256
	ds_write2_b64 v253, v[12:13], v[14:15] offset1:1
	ds_write2_b64 v254, v[16:17], v[18:19] offset1:1
	v_addc_co_u32_e32 v3, vcc, 0, v23, vcc
	s_mov_b32 s2, 0xd40a000
	global_load_dwordx4 v[144:147], v[0:1], off
	global_load_dwordx4 v[148:151], v[2:3], off
	v_add_co_u32_e32 v0, vcc, s2, v24
	v_mad_u32_u24 v213, v38, s29, 0
	s_nop 0
	v_addc_co_u32_e32 v1, vcc, 0, v25, vcc
	global_load_dwordx4 v[152:155], v[0:1], off
	global_load_dwordx4 v[156:159], v[28:29], off offset:128
	global_load_dwordx4 v[160:163], v[30:31], off offset:128
	s_movk_i32 s2, 0xfef8
	v_mad_i32_i24 v19, v38, s2, v213
	v_mad_u64_u32 v[16:17], s[2:3], v36, s29, v[32:33]
	v_readlane_b32 s2, v246, 47
	s_ashr_i32 s36, s42, 7
	v_lshlrev_b32_e32 v18, 3, v39
	v_mov_b32_e32 v0, s2
	s_mov_b64 s[2:3], 0xd40e000
	v_lshl_add_u64 v[188:189], v[24:25], 0, s[2:3]
	s_add_u32 s2, s40, s48
	s_addc_u32 s3, s41, s49
	v_mad_u32_u24 v17, v38, s68, v0
	v_lshl_add_u64 v[0:1], s[2:3], 0, v[26:27]
	s_mov_b64 s[2:3], 0x5a08180
	v_lshl_add_u64 v[190:191], v[0:1], 0, s[2:3]
	s_add_u32 s2, s26, s57
	s_addc_u32 s3, s27, s58
	v_lshl_add_u64 v[0:1], s[2:3], 0, v[20:21]
	s_mov_b64 s[2:3], 0x138e8000
	v_mov_b32_e32 v14, v185
	v_mov_b32_e32 v15, v185
	v_or_b32_e32 v214, s43, v38
	v_lshlrev_b32_e32 v212, 2, v39
	v_lshl_add_u64 v[192:193], v[0:1], 0, s[2:3]
	s_add_i32 s2, s36, s53
	v_mov_b32_e32 v0, v185
	v_mov_b32_e32 v1, v185
	v_mov_b32_e32 v2, v185
	v_mov_b32_e32 v3, v185
	v_mov_b32_e32 v4, v185
	v_mov_b32_e32 v5, v185
	v_mov_b32_e32 v6, v185
	v_mov_b32_e32 v7, v185
	v_mov_b32_e32 v8, v185
	v_mov_b32_e32 v9, v185
	v_mov_b32_e32 v10, v185
	v_mov_b32_e32 v11, v185
	v_mov_b32_e32 v12, v185
	v_mov_b32_e32 v13, v185
	v_add_u32_e32 v216, v19, v18
	v_add_u32_e32 v217, 0, v16
	v_add_u32_e32 v218, v17, v18
	v_mov_b64_e32 v[30:31], v[14:15]
	v_mov_b64_e32 v[46:47], v[14:15]
	v_mov_b64_e32 v[62:63], v[14:15]
	s_mov_b32 s20, 2
	s_sub_i32 s26, 1, s2
	s_sub_i32 s27, 0, s2
	v_mov_b32_e32 v194, 0xff800000
	v_mov_b32_e32 v196, 0
	v_mov_b32_e32 v197, 0
	v_mov_b32_e32 v198, 0
	v_mov_b32_e32 v199, 0
	v_mov_b32_e32 v200, 0
	v_mov_b32_e32 v201, 0
	v_mov_b32_e32 v202, 0
	v_mov_b32_e32 v203, 0
	v_mov_b32_e32 v204, 0
	v_mov_b32_e32 v205, 0
	v_mov_b32_e32 v206, 0
	v_mov_b32_e32 v207, 0
	v_mov_b32_e32 v208, 0
	v_mov_b32_e32 v209, 0
	v_mov_b32_e32 v210, 0
	v_mov_b32_e32 v211, 0
	v_mov_b32_e32 v215, 0
	v_mov_b32_e32 v219, v212
	v_mov_b64_e32 v[28:29], v[12:13]
	v_mov_b64_e32 v[26:27], v[10:11]
	v_mov_b64_e32 v[24:25], v[8:9]
	v_mov_b64_e32 v[22:23], v[6:7]
	v_mov_b64_e32 v[20:21], v[4:5]
	v_mov_b64_e32 v[18:19], v[2:3]
	v_mov_b64_e32 v[16:17], v[0:1]
	v_mov_b64_e32 v[44:45], v[12:13]
	v_mov_b64_e32 v[42:43], v[10:11]
	v_mov_b64_e32 v[40:41], v[8:9]
	v_mov_b64_e32 v[38:39], v[6:7]
	v_mov_b64_e32 v[36:37], v[4:5]
	v_mov_b64_e32 v[34:35], v[2:3]
	v_mov_b64_e32 v[32:33], v[0:1]
	v_mov_b64_e32 v[60:61], v[12:13]
	v_mov_b64_e32 v[58:59], v[10:11]
	v_mov_b64_e32 v[56:57], v[8:9]
	v_mov_b64_e32 v[54:55], v[6:7]
	v_mov_b64_e32 v[52:53], v[4:5]
	v_mov_b64_e32 v[50:51], v[2:3]
	v_mov_b64_e32 v[48:49], v[0:1]
	s_mov_b64 s[60:61], 0
	v_cmp_lt_u32_e32 vcc, 0xff, v195
	s_cbranch_vccnz .Lattn_pro2_skip
	v_add_co_u32_e32 v64, vcc, 0xfffa0000, v192
	s_nop 1
	v_addc_co_u32_e32 v65, vcc, -1, v193, vcc
	v_add_co_u32_e32 v66, vcc, 0xfffc0000, v192
	s_nop 1
	v_addc_co_u32_e32 v67, vcc, -1, v193, vcc
	global_load_dwordx4 v[164:167], v[64:65], off
	global_load_dwordx4 v[168:171], v[66:67], off
	v_add_co_u32_e32 v64, vcc, 0xffffe000, v188
	s_nop 1
	v_addc_co_u32_e32 v65, vcc, -1, v189, vcc
	global_load_dwordx4 v[172:175], v[64:65], off
	v_add_co_u32_e32 v64, vcc, 0xffdfff80, v190
	s_nop 1
	v_addc_co_u32_e32 v65, vcc, -1, v191, vcc
	v_add_co_u32_e32 v66, vcc, 0xffffff80, v190
	s_nop 1
	v_addc_co_u32_e32 v67, vcc, -1, v191, vcc
	global_load_dwordx4 v[176:179], v[64:65], off
	global_load_dwordx4 v[180:183], v[66:67], off

; #define ATT_LOAD(kr, vr, t) do { const bf16_t* kp_ = KVb + (size_t)(t) * 64 * 2048 + kn_off; \
;         kr[0] = *(const u32x4*)kp_; kr[1] = *(const u32x4*)(kp_ + 32 * 2048); kr[2] = *(const u32x4*)(KPEb + (t) * 64 * 64 + kp_off); \
;         const bf16_t* vp_ = VTb + (t) * 64 + v_off; vr[0] = *(const u32x4*)vp_; vr[1] = *(const u32x4*)(vp_ + 64 * SEQ); } while (0)
; #define ATT_TILE(t, slot) do { const int rel_ = (t) - 4 * qb; if (rel_ <= (w >> 1)) { qk_softmax((t), (slot), rel_ == (w >> 1)); pv(slot); } } while (0)
; DI void attn_unit(const Params& P, LAS unsigned char* lds, int b, int h, int qb, bool dry) {
;     ...
;     ATT_LOAD(kA, vA, 0);
;     __syncthreads();
;     ATT_STORE(kA, vA, 0);
;     ATT_LOAD(kA, vA, 1);
;     __syncthreads();
;     for (int kt = 0; kt < nt; kt += 2) {
;         const bool more2 = kt + 2 < nt;
;         if (more2) ATT_LOAD(kB, vB, kt + 2);
;         ATT_TILE(kt, 0);
;         ATT_STORE(kA, vA, 1);
;         __syncthreads();
;         if (more2) ATT_LOAD(kA, vA, kt + 3);
;         ATT_TILE(kt + 1, 1);
;         if (more2) ATT_STORE(kB, vB, 0);
;         __syncthreads();
;     }
.LBB0_52:
	s_mov_b64 s[30:31], 0x100
	v_lshl_add_u64 v[190:191], v[190:191], 0, s[30:31]
	s_mov_b64 s[30:31], 0x80000
	v_add_u32_e32 v219, 0x80, v219
	v_lshl_add_u64 v[188:189], v[188:189], 0, s[96:97]
	v_lshl_add_u64 v[192:193], v[192:193], 0, s[30:31]
	s_add_i32 s20, s20, 2
	s_waitcnt lgkmcnt(0)
	s_cmp_lt_u32 s20, s35
	s_cbranch_scc0 .Lattn_pfB2_skip
	v_cmp_lt_u32_e32 vcc, 0xff, v195
	s_cbranch_vccnz .Lattn_pfB2_skip
	v_add_co_u32_e32 v64, vcc, 0xfffa0000, v192
	s_nop 1
	v_addc_co_u32_e32 v65, vcc, -1, v193, vcc
	v_add_co_u32_e32 v66, vcc, 0xfffc0000, v192
	s_nop 1
	v_addc_co_u32_e32 v67, vcc, -1, v193, vcc
	global_load_dwordx4 v[164:167], v[64:65], off
	global_load_dwordx4 v[168:171], v[66:67], off
	v_add_co_u32_e32 v64, vcc, 0xffffe000, v188
	s_nop 1
	v_addc_co_u32_e32 v65, vcc, -1, v189, vcc
	global_load_dwordx4 v[172:175], v[64:65], off
	v_add_co_u32_e32 v64, vcc, 0xffdfff80, v190
	s_nop 1
	v_addc_co_u32_e32 v65, vcc, -1, v191, vcc
	v_add_co_u32_e32 v66, vcc, 0xffffff80, v190
	s_nop 1
	v_addc_co_u32_e32 v67, vcc, -1, v191, vcc
	global_load_dwordx4 v[176:179], v[64:65], off
	global_load_dwordx4 v[180:183], v[66:67], off

; #define ATT_LOAD(kr, vr, t) do { const bf16_t* kp_ = KVb + (size_t)(t) * 64 * 2048 + kn_off; \
;         kr[0] = *(const u32x4*)kp_; kr[1] = *(const u32x4*)(kp_ + 32 * 2048); kr[2] = *(const u32x4*)(KPEb + (t) * 64 * 64 + kp_off); \
;         const bf16_t* vp_ = VTb + (t) * 64 + v_off; vr[0] = *(const u32x4*)vp_; vr[1] = *(const u32x4*)(vp_ + 64 * SEQ); } while (0)
; DI void attn_unit(const Params& P, LAS unsigned char* lds, int b, int h, int qb, bool dry) {
;     ...
;     ATT_LOAD(kA, vA, 0);
;     __syncthreads();
;     ATT_STORE(kA, vA, 0);
;     ATT_LOAD(kA, vA, 1);
;     __syncthreads();
;     for (int kt = 0; kt < nt; kt += 2) {
;         const bool more2 = kt + 2 < nt;
;         if (more2) ATT_LOAD(kB, vB, kt + 2);
.LBB0_53:
	s_cmp_lt_u32 s20, s35
	s_cselect_b64 s[30:31], -1, 0
	s_cmp_ge_u32 s20, s35
	s_cselect_b64 s[2:3], -1, 0
	s_and_b64 vcc, exec, s[2:3]
	s_cbranch_vccnz .LBB0_55
	v_cmp_lt_u32_e32 vcc, 0xff, v195
	s_cbranch_vccz .LBB0_55
	v_add_co_u32_e32 v64, vcc, 0xfffa0000, v192
	s_nop 1
	v_addc_co_u32_e32 v65, vcc, -1, v193, vcc
	v_add_co_u32_e32 v66, vcc, 0xfffc0000, v192
	s_nop 1
	v_addc_co_u32_e32 v67, vcc, -1, v193, vcc
	global_load_dwordx4 v[164:167], v[64:65], off
	global_load_dwordx4 v[168:171], v[66:67], off
	v_add_co_u32_e32 v64, vcc, 0xffffe000, v188
	s_nop 1
	v_addc_co_u32_e32 v65, vcc, -1, v189, vcc
	global_load_dwordx4 v[172:175], v[64:65], off
	v_add_co_u32_e32 v64, vcc, 0xffdfff80, v190
	s_nop 1
	v_addc_co_u32_e32 v65, vcc, -1, v191, vcc
	v_add_co_u32_e32 v66, vcc, 0xffffff80, v190
	s_nop 1
	v_addc_co_u32_e32 v67, vcc, -1, v191, vcc
	global_load_dwordx4 v[176:179], v[64:65], off
	global_load_dwordx4 v[180:183], v[66:67], off

; #define ATT_LOAD(kr, vr, t) do { const bf16_t* kp_ = KVb + (size_t)(t) * 64 * 2048 + kn_off; \
;         kr[0] = *(const u32x4*)kp_; kr[1] = *(const u32x4*)(kp_ + 32 * 2048); kr[2] = *(const u32x4*)(KPEb + (t) * 64 * 64 + kp_off); \
;         const bf16_t* vp_ = VTb + (t) * 64 + v_off; vr[0] = *(const u32x4*)vp_; vr[1] = *(const u32x4*)(vp_ + 64 * SEQ); } while (0)
; #define ATT_TILE(t, slot) do { const int rel_ = (t) - 4 * qb; if (rel_ <= (w >> 1)) { qk_softmax((t), (slot), rel_ == (w >> 1)); pv(slot); } } while (0)
; DI void attn_unit(const Params& P, LAS unsigned char* lds, int b, int h, int qb, bool dry) {
;     ...
;     ATT_LOAD(kA, vA, 0);
;     __syncthreads();
;     ATT_STORE(kA, vA, 0);
;     ATT_LOAD(kA, vA, 1);
;     __syncthreads();
;     for (int kt = 0; kt < nt; kt += 2) {
;         const bool more2 = kt + 2 < nt;
;         if (more2) ATT_LOAD(kB, vB, kt + 2);
;         ATT_TILE(kt, 0);
;         ATT_STORE(kA, vA, 1);
;         __syncthreads();
;         if (more2) ATT_LOAD(kA, vA, kt + 3);
;         ATT_TILE(kt + 1, 1);
.Lattn_wdone2:
	s_not_b64 s[40:41], s[30:31]
	s_waitcnt lgkmcnt(0)
	s_mov_b64 vcc, s[30:31]
	s_cbranch_vccz .Lattn_pfA2_skip
	v_cmp_lt_u32_e32 vcc, 0xff, v195
	s_cbranch_vccnz .Lattn_pfA2_skip
	v_add_co_u32_e32 v64, vcc, 0xfffe0000, v192
	s_nop 1
	v_addc_co_u32_e32 v65, vcc, -1, v193, vcc
	global_load_dwordx4 v[144:147], v[64:65], off
	global_load_dwordx4 v[148:151], v[192:193], off
	global_load_dwordx4 v[152:155], v[188:189], off
	v_add_co_u32_e32 v64, vcc, 0xffe00000, v190
	s_nop 1
	v_addc_co_u32_e32 v65, vcc, -1, v191, vcc
	global_load_dwordx4 v[156:159], v[64:65], off
	global_load_dwordx4 v[160:163], v[190:191], off
.Lattn_pfA2_skip:
	s_andn2_b64 vcc, exec, s[30:31]
	s_barrier
	s_cbranch_vccnz .LBB0_64
	v_cmp_lt_u32_e32 vcc, 0xff, v195
	s_cbranch_vccz .Lattn_pfA2_b
	v_add_co_u32_e32 v64, vcc, 0xfffe0000, v192
	s_nop 1
	v_addc_co_u32_e32 v65, vcc, -1, v193, vcc
	global_load_dwordx4 v[144:147], v[64:65], off
	global_load_dwordx4 v[148:151], v[192:193], off
	global_load_dwordx4 v[152:155], v[188:189], off
	v_add_co_u32_e32 v64, vcc, 0xffe00000, v190
	s_nop 1
	v_addc_co_u32_e32 v65, vcc, -1, v191, vcc
	global_load_dwordx4 v[156:159], v[64:65], off
	global_load_dwordx4 v[160:163], v[190:191], off
.Lattn_pfA2_b:
	s_add_i32 s37, s37, -1
	s_cmp_gt_i32 s37, s36
	s_cbranch_scc0 .LBB0_65
